# prep_row H/L/SS stores write-through (sc1) so the grid sync's L2 writeback has nothing to flush
# baseline (speedup 1.0000x reference)
; __device__ __forceinline__ void prep_row(const float* xrow, bf16* hrow, bf16* lrow, float* ssrow, int lane) {
;     float ss = 0.f;
; #pragma unroll
;     for (int j = 0; j < 8; ++j) {
;         const f32x4 v = *(const f32x4*)(xrow + 4 * lane + 256 * j);
;         ss += (v.x * v.x + v.y * v.y) + (v.z * v.z + v.w * v.w);
;         u32x2 o; o.x = cvtpk(v.x, v.y); o.y = cvtpk(v.z, v.w);
;         u32x2 lo; lo.x = cvtpk(v.x - bflo(o.x), v.y - bfhi(o.x)); lo.y = cvtpk(v.z - bflo(o.y), v.w - bfhi(o.y));
;         *(u32x2*)(hrow + 4 * lane + 256 * j) = o; *(u32x2*)(lrow + 4 * lane + 256 * j) = lo;
;     }
.LBB0_200:
	v_add_co_u32_e32 v22, vcc, 0xfffff000, v10
	v_lshl_add_u64 v[34:35], s[62:63], 0, v[8:9]
	s_nop 0
	v_addc_co_u32_e32 v23, vcc, -1, v11, vcc
	s_waitcnt lgkmcnt(0)
	global_load_dwordx4 v[2:5], v[22:23], off offset:-3072
	v_add_co_u32_e32 v30, vcc, s2, v34
	s_waitcnt vmcnt(0)
	v_cvt_pk_bf16_f32 v18, v2, v3
	v_cvt_pk_bf16_f32 v19, v4, v5
	v_addc_co_u32_e32 v31, vcc, 0, v35, vcc
	v_lshlrev_b32_e32 v20, 16, v18
	v_and_b32_e32 v21, 0xffff0000, v18
	v_lshlrev_b32_e32 v24, 16, v19
	v_and_b32_e32 v25, 0xffff0000, v19
	v_add_co_u32_e32 v32, vcc, s3, v34
	global_store_dwordx2 v[30:31], v[18:19], off offset:2048 sc1
	v_pk_add_f32 v[18:19], v[2:3], v[20:21] neg_lo:[0,1] neg_hi:[0,1]
	v_pk_add_f32 v[20:21], v[4:5], v[24:25] neg_lo:[0,1] neg_hi:[0,1]
	v_addc_co_u32_e32 v33, vcc, 0, v35, vcc
	v_cvt_pk_bf16_f32 v18, v18, v19
	v_cvt_pk_bf16_f32 v19, v20, v21
	global_store_dwordx2 v[32:33], v[18:19], off offset:2048 sc1
	global_load_dwordx4 v[18:21], v[22:23], off offset:-2048
	v_add_co_u32_e32 v46, vcc, s16, v34
	v_mul_f32_e32 v3, v3, v3
	s_nop 0
	v_addc_co_u32_e32 v47, vcc, 0, v35, vcc
	v_add_co_u32_e32 v48, vcc, s17, v34
	v_mul_f32_e32 v5, v5, v5
	s_nop 0
	v_addc_co_u32_e32 v49, vcc, 0, v35, vcc
	v_fmac_f32_e32 v3, v2, v2
	v_fmac_f32_e32 v5, v4, v4
	v_add_f32_e32 v2, v3, v5
	s_waitcnt vmcnt(0)
	v_cvt_pk_bf16_f32 v24, v18, v19
	v_cvt_pk_bf16_f32 v25, v20, v21
	v_lshlrev_b32_e32 v26, 16, v24
	v_and_b32_e32 v27, 0xffff0000, v24
	v_lshlrev_b32_e32 v28, 16, v25
	v_and_b32_e32 v29, 0xffff0000, v25
	global_store_dwordx2 v[30:31], v[24:25], off offset:2560 sc1
	v_pk_add_f32 v[24:25], v[18:19], v[26:27] neg_lo:[0,1] neg_hi:[0,1]
	v_pk_add_f32 v[26:27], v[20:21], v[28:29] neg_lo:[0,1] neg_hi:[0,1]
	v_cvt_pk_bf16_f32 v24, v24, v25
	v_cvt_pk_bf16_f32 v25, v26, v27
	global_store_dwordx2 v[32:33], v[24:25], off offset:2560 sc1
	global_load_dwordx4 v[22:25], v[22:23], off offset:-1024
	v_mul_f32_e32 v3, v19, v19
	v_mul_f32_e32 v4, v21, v21
	v_fmac_f32_e32 v3, v18, v18
	v_fmac_f32_e32 v4, v20, v20
	v_add_f32_e32 v3, v3, v4
	v_add_f32_e32 v2, v2, v3
	s_waitcnt vmcnt(0)
	v_cvt_pk_bf16_f32 v26, v22, v23
	v_cvt_pk_bf16_f32 v27, v24, v25
	v_lshlrev_b32_e32 v28, 16, v26
	v_and_b32_e32 v29, 0xffff0000, v26
	v_lshlrev_b32_e32 v36, 16, v27
	v_and_b32_e32 v37, 0xffff0000, v27
	global_store_dwordx2 v[30:31], v[26:27], off offset:3072 sc1
	v_pk_add_f32 v[26:27], v[22:23], v[28:29] neg_lo:[0,1] neg_hi:[0,1]
	v_pk_add_f32 v[28:29], v[24:25], v[36:37] neg_lo:[0,1] neg_hi:[0,1]
	v_cvt_pk_bf16_f32 v26, v26, v27
	v_cvt_pk_bf16_f32 v27, v28, v29
	global_store_dwordx2 v[32:33], v[26:27], off offset:3072 sc1
	global_load_dwordx4 v[26:29], v[10:11], off offset:-4096
	v_mul_f32_e32 v3, v23, v23
	v_mul_f32_e32 v4, v25, v25
	v_fmac_f32_e32 v3, v22, v22
	v_fmac_f32_e32 v4, v24, v24
	v_add_f32_e32 v3, v3, v4
	v_add_f32_e32 v2, v2, v3
	s_waitcnt vmcnt(0)
	v_cvt_pk_bf16_f32 v36, v26, v27
	v_cvt_pk_bf16_f32 v37, v28, v29
	v_lshlrev_b32_e32 v38, 16, v36
	v_and_b32_e32 v39, 0xffff0000, v36
	v_lshlrev_b32_e32 v40, 16, v37
	v_and_b32_e32 v41, 0xffff0000, v37
	global_store_dwordx2 v[30:31], v[36:37], off offset:3584 sc1
	v_pk_add_f32 v[30:31], v[26:27], v[38:39] neg_lo:[0,1] neg_hi:[0,1]
	v_pk_add_f32 v[36:37], v[28:29], v[40:41] neg_lo:[0,1] neg_hi:[0,1]
	v_cvt_pk_bf16_f32 v30, v30, v31
	v_cvt_pk_bf16_f32 v31, v36, v37
	global_store_dwordx2 v[32:33], v[30:31], off offset:3584 sc1
	global_load_dwordx4 v[30:33], v[10:11], off offset:-3072
	v_mul_f32_e32 v3, v27, v27
	v_mul_f32_e32 v4, v29, v29
	v_fmac_f32_e32 v3, v26, v26
	v_fmac_f32_e32 v4, v28, v28
	v_add_f32_e32 v3, v3, v4
	v_add_f32_e32 v2, v2, v3
	s_waitcnt vmcnt(0)
; __device__ __forceinline__ void prep_row(const float* xrow, bf16* hrow, bf16* lrow, float* ssrow, int lane) {
;     ...
;     for (int j = 0; j < 8; ++j) {
;         const f32x4 v = *(const f32x4*)(xrow + 4 * lane + 256 * j);
;         ss += (v.x * v.x + v.y * v.y) + (v.z * v.z + v.w * v.w);
;         u32x2 o; o.x = cvtpk(v.x, v.y); o.y = cvtpk(v.z, v.w);
;         u32x2 lo; lo.x = cvtpk(v.x - bflo(o.x), v.y - bfhi(o.x)); lo.y = cvtpk(v.z - bflo(o.y), v.w - bfhi(o.y));
;         *(u32x2*)(hrow + 4 * lane + 256 * j) = o; *(u32x2*)(lrow + 4 * lane + 256 * j) = lo;
;     }
;     ss = wave_sum(ss);
;     if (lane < 8) ssrow[lane] = lane == 0 ? ss : 0.f;
	v_cvt_pk_bf16_f32 v34, v30, v31
	v_cvt_pk_bf16_f32 v35, v32, v33
	v_lshlrev_b32_e32 v36, 16, v34
	v_and_b32_e32 v37, 0xffff0000, v34
	v_lshlrev_b32_e32 v38, 16, v35
	v_and_b32_e32 v39, 0xffff0000, v35
	global_store_dwordx2 v[46:47], v[34:35], off sc1
	v_pk_add_f32 v[34:35], v[30:31], v[36:37] neg_lo:[0,1] neg_hi:[0,1]
	v_pk_add_f32 v[36:37], v[32:33], v[38:39] neg_lo:[0,1] neg_hi:[0,1]
	v_cvt_pk_bf16_f32 v34, v34, v35
	v_cvt_pk_bf16_f32 v35, v36, v37
	global_store_dwordx2 v[48:49], v[34:35], off sc1
	global_load_dwordx4 v[34:37], v[10:11], off offset:-2048
	v_mul_f32_e32 v3, v31, v31
	v_mul_f32_e32 v4, v33, v33
	v_fmac_f32_e32 v3, v30, v30
	v_fmac_f32_e32 v4, v32, v32
	v_add_f32_e32 v3, v3, v4
	v_add_f32_e32 v2, v2, v3
	s_waitcnt vmcnt(0)
	v_cvt_pk_bf16_f32 v38, v34, v35
	v_cvt_pk_bf16_f32 v39, v36, v37
	v_lshlrev_b32_e32 v40, 16, v38
	v_and_b32_e32 v41, 0xffff0000, v38
	v_lshlrev_b32_e32 v42, 16, v39
	v_and_b32_e32 v43, 0xffff0000, v39
	global_store_dwordx2 v[46:47], v[38:39], off offset:512 sc1
	v_pk_add_f32 v[38:39], v[34:35], v[40:41] neg_lo:[0,1] neg_hi:[0,1]
	v_pk_add_f32 v[40:41], v[36:37], v[42:43] neg_lo:[0,1] neg_hi:[0,1]
	v_cvt_pk_bf16_f32 v38, v38, v39
	v_cvt_pk_bf16_f32 v39, v40, v41
	global_store_dwordx2 v[48:49], v[38:39], off offset:512 sc1
	global_load_dwordx4 v[38:41], v[10:11], off offset:-1024
	v_mul_f32_e32 v3, v35, v35
	v_mul_f32_e32 v4, v37, v37
	v_fmac_f32_e32 v3, v34, v34
	v_fmac_f32_e32 v4, v36, v36
	v_add_f32_e32 v3, v3, v4
	v_add_f32_e32 v2, v2, v3
	s_waitcnt vmcnt(0)
	v_cvt_pk_bf16_f32 v42, v38, v39
	v_cvt_pk_bf16_f32 v43, v40, v41
	v_lshlrev_b32_e32 v44, 16, v42
	v_and_b32_e32 v45, 0xffff0000, v42
	v_lshlrev_b32_e32 v50, 16, v43
	v_and_b32_e32 v51, 0xffff0000, v43
	global_store_dwordx2 v[46:47], v[42:43], off offset:1024 sc1
	v_pk_add_f32 v[42:43], v[38:39], v[44:45] neg_lo:[0,1] neg_hi:[0,1]
	v_pk_add_f32 v[44:45], v[40:41], v[50:51] neg_lo:[0,1] neg_hi:[0,1]
	v_cvt_pk_bf16_f32 v42, v42, v43
	v_cvt_pk_bf16_f32 v43, v44, v45
	global_store_dwordx2 v[48:49], v[42:43], off offset:1024 sc1
	global_load_dwordx4 v[42:45], v[10:11], off
	v_mul_f32_e32 v3, v39, v39
	v_mul_f32_e32 v4, v41, v41
	v_fmac_f32_e32 v3, v38, v38
	v_fmac_f32_e32 v4, v40, v40
	v_add_f32_e32 v3, v3, v4
	v_add_f32_e32 v2, v2, v3
	s_waitcnt vmcnt(0)
	v_mul_f32_e32 v3, v43, v43
	v_mul_f32_e32 v4, v45, v45
	v_fmac_f32_e32 v3, v42, v42
	v_fmac_f32_e32 v4, v44, v44
	v_add_f32_e32 v3, v3, v4
	v_add_f32_e32 v2, v2, v3
	ds_bpermute_b32 v3, v1, v2
	v_cvt_pk_bf16_f32 v4, v42, v43
	v_cvt_pk_bf16_f32 v5, v44, v45
	v_lshlrev_b32_e32 v20, 16, v5
	v_and_b32_e32 v21, 0xffff0000, v5
	s_waitcnt lgkmcnt(0)
	v_add_f32_e32 v2, v2, v3
	ds_bpermute_b32 v3, v13, v2
	v_pk_add_f32 v[20:21], v[44:45], v[20:21] neg_lo:[0,1] neg_hi:[0,1]
	s_waitcnt lgkmcnt(0)
	v_add_f32_e32 v2, v2, v3
	ds_bpermute_b32 v3, v14, v2
	s_waitcnt lgkmcnt(0)
	v_add_f32_e32 v18, v2, v3
	ds_bpermute_b32 v19, v15, v18
	v_lshlrev_b32_e32 v2, 16, v4
	v_and_b32_e32 v3, 0xffff0000, v4
	v_pk_add_f32 v[2:3], v[42:43], v[2:3] neg_lo:[0,1] neg_hi:[0,1]
	s_waitcnt lgkmcnt(0)
	v_add_f32_e32 v19, v18, v19
	ds_bpermute_b32 v22, v16, v19
	v_cvt_pk_bf16_f32 v18, v2, v3
	s_waitcnt lgkmcnt(0)
	v_add_f32_e32 v2, v19, v22
	ds_bpermute_b32 v3, v17, v2
	v_cvt_pk_bf16_f32 v19, v20, v21
	global_store_dwordx2 v[46:47], v[4:5], off offset:1536 sc1
	global_store_dwordx2 v[48:49], v[18:19], off offset:1536 sc1
	s_and_saveexec_b64 s[14:15], s[6:7]
	s_cbranch_execz .LBB0_199
	s_waitcnt lgkmcnt(0)
	v_add_f32_e32 v2, v2, v3
	v_cndmask_b32_e64 v4, 0, v2, s[4:5]
	v_lshl_add_u64 v[2:3], s[62:63], 0, v[6:7]
	global_store_dword v[2:3], v4, off sc1
	s_branch .LBB0_199
